# P8 and P6 epilogues: row-sumsq float atomics deferred to the end of the epilogue (in-order vmcnt no longer queues residual-load waits behind them)
# speedup vs baseline: 1.0018x; 1.0018x over previous
; __device__ __forceinline__ unsigned pk2(float lo, float hi) { f32x2_t v = {lo, hi}; bf16x2_t b = __builtin_convertvector(v, bf16x2_t); return __builtin_bit_cast(unsigned, b); }
;     __device__ __forceinline__ void load(int row, int col, Pre& p) const { const size_t off = (size_t)row * 2048 + col;
;     ...
;         const u32x4 w = *(const u32x4*)(HB + off);
;         p.x0 = (f32x4){bflo(w.x), bfhi(w.x), bflo(w.y), bfhi(w.y)}; p.x1 = (f32x4){bflo(w.z), bfhi(w.z), bflo(w.w), bfhi(w.w)};
;     ...
;         p.x0 = __builtin_nontemporal_load((const f32x4*)(x + off)); p.x1 = __builtin_nontemporal_load((const f32x4*)(x + off + 4));
;     ...
;     }
;     __device__ __forceinline__ float apply(int row, int col, float (&v)[8], const Pre& p) const {
;         const size_t off = (size_t)row * 2048 + col;
;         f32x4 h0, h1; float s = 0.f;
; #pragma unroll
;         for (int i = 0; i < 4; ++i) { h0[i] = p.x0[i] + v[i]; h1[i] = p.x1[i] + v[4 + i]; s += h0[i] * h0[i] + h1[i] * h1[i]; }
;     ...
;         *(f32x4*)(H1 + off) = h0; *(f32x4*)(H1 + off + 4) = h1;
;     ...
;         u32x4 w; w.x = pk2(h0[0], h0[1]); w.y = pk2(h0[2], h0[3]); w.z = pk2(h1[0], h1[1]); w.w = pk2(h1[2], h1[3]);
;         *(u32x4*)(HB + off) = w;
;         return s;
;     __device__ __forceinline__ void operator()(const pg8::f32x4 (&acc)[2][2][4][2], const pg8::Unit& u, int wr, int wc, int fr, int fq) const {
;     ...
;         f.load(row0, col0, pa[0]); f.load(row0, col0 + 128, pa[1]);
; #pragma unroll
;         for (int g = 0; g < 8; ++g) {
;             const int ai = g >> 2, m = g & 3, row = row0 + ai * 128 + m * 16;
;             if (g < 7) { const int row2 = row0 + ((g + 1) >> 2) * 128 + ((g + 1) & 3) * 16;
;                 if (g & 1) { f.load(row2, col0, pa[0]); f.load(row2, col0 + 128, pa[1]); } else { f.load(row2, col0, pb[0]); f.load(row2, col0 + 128, pb[1]); } }
;             float ss = 0.f;
; #pragma unroll
;             for (int bj = 0; bj < 2; ++bj) {
;                 float v[8] = {acc[ai][bj][m][0][0], acc[ai][bj][m][0][1], acc[ai][bj][m][0][2], acc[ai][bj][m][0][3], acc[ai][bj][m][1][0], acc[ai][bj][m][1][1], acc[ai][bj][m][1][2], acc[ai][bj][m][1][3]};
;                 ss += f.apply(row, col0 + bj * 128, v, (g & 1) ? pb[bj] : pa[bj]);
;             }
;             if (F::HAS_SS) { ss += __shfl_xor(ss, 16); ss += __shfl_xor(ss, 32); if (fq == 0) atomicAdd(f.ss + row, ss); }
.LBB0_967:
	v_lshl_add_u32 v154, s2, 8, v158
	v_lshl_or_b32 v152, s24, 8, v160
	v_ashrrev_i32_e32 v155, 31, v154
	v_ashrrev_i32_e32 v153, 31, v152
	v_lshlrev_b64 v[128:129], 12, v[154:155]
	v_lshl_add_u64 v[128:129], s[82:83], 0, v[128:129]
	v_lshlrev_b64 v[130:131], 1, v[152:153]
	v_lshl_add_u64 v[176:177], v[128:129], 0, v[130:131]
	global_load_dwordx4 v[168:171], v[176:177], off
	global_load_dwordx4 v[172:175], v[176:177], off offset:256
	v_or_b32_e32 v128, 16, v154
	v_ashrrev_i32_e32 v129, 31, v128
	v_lshlrev_b64 v[128:129], 12, v[128:129]
	v_lshl_add_u64 v[128:129], s[82:83], 0, v[128:129]
	v_lshl_add_u64 v[156:157], v[128:129], 0, v[130:131]
	global_load_dwordx4 v[132:135], v[156:157], off
	global_load_dwordx4 v[128:131], v[156:157], off offset:256
	v_and_b32_e32 v166, 64, v164
	v_xor_b32_e32 v165, 16, v164
	v_add_u32_e32 v166, 64, v166
	v_cmp_lt_i32_e32 vcc, v165, v166
	v_xor_b32_e32 v167, 32, v164
	s_waitcnt vmcnt(0)
	v_lshlrev_b32_e32 v178, 16, v168
	v_and_b32_e32 v179, 0xffff0000, v168
	v_lshlrev_b32_e32 v180, 16, v170
	v_and_b32_e32 v181, 0xffff0000, v170
	v_lshlrev_b32_e32 v168, 16, v169
	v_and_b32_e32 v169, 0xffff0000, v169
	v_lshlrev_b32_e32 v188, 16, v174
	v_and_b32_e32 v189, 0xffff0000, v174
	v_lshlrev_b32_e32 v170, 16, v171
	v_and_b32_e32 v171, 0xffff0000, v171
	v_lshlrev_b32_e32 v182, 16, v172
	v_and_b32_e32 v183, 0xffff0000, v172
	v_lshlrev_b32_e32 v172, 16, v173
	v_and_b32_e32 v173, 0xffff0000, v173
	v_lshlrev_b32_e32 v174, 16, v175
	v_and_b32_e32 v175, 0xffff0000, v175
	v_pk_add_f32 v[120:121], v[120:121], v[180:181]
	v_pk_add_f32 v[126:127], v[126:127], v[168:169]
	v_pk_add_f32 v[168:169], v[112:113], v[188:189]
	v_pk_add_f32 v[124:125], v[124:125], v[178:179]
	v_pk_add_f32 v[122:123], v[122:123], v[170:171]
	v_pk_add_f32 v[116:117], v[116:117], v[182:183]
	v_pk_add_f32 v[118:119], v[118:119], v[172:173]
	v_pk_add_f32 v[170:171], v[114:115], v[174:175]
	v_pk_mul_f32 v[172:173], v[120:121], v[120:121]
	v_cvt_pk_bf16_f32 v114, v120, v121
	v_pk_mul_f32 v[120:121], v[168:169], v[168:169]
	v_pk_mul_f32 v[174:175], v[122:123], v[122:123]
	v_cvt_pk_bf16_f32 v112, v124, v125
	v_pk_mul_f32 v[178:179], v[170:171], v[170:171]
	v_pk_fma_f32 v[124:125], v[124:125], v[124:125], v[172:173]
	v_pk_fma_f32 v[120:121], v[116:117], v[116:117], v[120:121]
	v_cvt_pk_bf16_f32 v113, v126, v127
	v_pk_fma_f32 v[126:127], v[126:127], v[126:127], v[174:175]
	v_pk_fma_f32 v[172:173], v[118:119], v[118:119], v[178:179]
	v_add_f32_e32 v115, v120, v121
	v_add_f32_e32 v120, v124, v125
	v_add_f32_e32 v115, v172, v115
	v_add_f32_e32 v120, v126, v120
	v_cndmask_b32_e32 v165, v164, v165, vcc
	v_add_f32_e32 v115, v173, v115
	v_add_f32_e32 v120, v127, v120
	v_cmp_lt_i32_e32 vcc, v167, v166
	v_lshlrev_b32_e32 v166, 2, v165
	v_add_f32_e32 v120, v120, v115
	ds_bpermute_b32 v121, v166, v120
	v_cndmask_b32_e32 v167, v164, v167, vcc
	v_cvt_pk_bf16_f32 v115, v122, v123
	v_lshlrev_b32_e32 v165, 2, v167
	global_store_dwordx4 v[176:177], v[112:115], off
	s_waitcnt lgkmcnt(0)
	s_nop 0
	v_add_f32_e32 v112, v120, v121
	ds_bpermute_b32 v113, v165, v112
	v_cvt_pk_bf16_f32 v114, v116, v117
	v_cvt_pk_bf16_f32 v115, v118, v119
	v_cvt_pk_bf16_f32 v116, v168, v169
	v_cvt_pk_bf16_f32 v117, v170, v171
	v_lshl_add_u64 v[120:121], v[154:155], 2, s[88:89]
	global_store_dwordx4 v[176:177], v[114:117], off offset:256
	s_and_saveexec_b64 s[2:3], s[4:5]
	s_cbranch_execz .LBB0_969
	s_waitcnt lgkmcnt(0)
	v_add_f32_e32 v112, v112, v113
	v_mov_b32_e32 v230, v112
.LBB0_969:
	s_or_b64 exec, exec, s[2:3]
	v_or_b32_e32 v112, 32, v154
	s_waitcnt lgkmcnt(0)
	v_ashrrev_i32_e32 v113, 31, v112
	v_lshlrev_b64 v[112:113], 12, v[112:113]
	v_lshl_add_u64 v[112:113], s[82:83], 0, v[112:113]
	v_lshl_add_u64 v[122:123], v[152:153], 1, v[112:113]
	global_load_dwordx4 v[116:119], v[122:123], off
	global_load_dwordx4 v[112:115], v[122:123], off offset:256
	v_lshlrev_b32_e32 v124, 16, v132
	v_and_b32_e32 v125, 0xffff0000, v132
	v_lshlrev_b32_e32 v126, 16, v133
	v_and_b32_e32 v127, 0xffff0000, v133
	v_lshlrev_b32_e32 v132, 16, v134
	v_and_b32_e32 v133, 0xffff0000, v134
	v_lshlrev_b32_e32 v134, 16, v135
	v_and_b32_e32 v135, 0xffff0000, v135
	v_pk_add_f32 v[108:109], v[108:109], v[124:125]
	v_pk_add_f32 v[124:125], v[104:105], v[132:133]
	v_pk_add_f32 v[110:111], v[110:111], v[126:127]
	v_pk_mul_f32 v[104:105], v[124:125], v[124:125]
	v_pk_add_f32 v[126:127], v[106:107], v[134:135]
	v_lshlrev_b32_e32 v170, 16, v130
	v_and_b32_e32 v171, 0xffff0000, v130
	v_pk_fma_f32 v[132:133], v[108:109], v[108:109], v[104:105]
	v_pk_mul_f32 v[104:105], v[126:127], v[126:127]
	v_lshlrev_b32_e32 v168, 16, v128
	v_and_b32_e32 v169, 0xffff0000, v128
	v_lshlrev_b32_e32 v130, 16, v131
	v_and_b32_e32 v131, 0xffff0000, v131
	v_pk_fma_f32 v[106:107], v[110:111], v[110:111], v[104:105]
	v_cvt_pk_bf16_f32 v104, v108, v109
	v_pk_add_f32 v[108:109], v[96:97], v[170:171]
	v_lshlrev_b32_e32 v128, 16, v129
	v_and_b32_e32 v129, 0xffff0000, v129
	v_cvt_pk_bf16_f32 v105, v110, v111
	v_pk_add_f32 v[100:101], v[100:101], v[168:169]
	v_pk_mul_f32 v[96:97], v[108:109], v[108:109]
	v_pk_add_f32 v[110:111], v[98:99], v[130:131]
	v_pk_fma_f32 v[96:97], v[100:101], v[100:101], v[96:97]
	v_pk_add_f32 v[102:103], v[102:103], v[128:129]
	v_pk_mul_f32 v[98:99], v[110:111], v[110:111]
	v_add_f32_e32 v96, v96, v97
	v_pk_fma_f32 v[98:99], v[102:103], v[102:103], v[98:99]
	v_add_f32_e32 v97, v132, v133
	v_add_f32_e32 v96, v98, v96
	v_add_f32_e32 v97, v106, v97
	v_add_f32_e32 v96, v99, v96
	v_add_f32_e32 v97, v107, v97
	v_add_f32_e32 v96, v97, v96
	ds_bpermute_b32 v97, v166, v96
	v_cvt_pk_bf16_f32 v106, v124, v125
	v_cvt_pk_bf16_f32 v107, v126, v127
	v_cvt_pk_bf16_f32 v98, v100, v101
	v_cvt_pk_bf16_f32 v99, v102, v103
	s_waitcnt lgkmcnt(0)
	v_add_f32_e32 v96, v96, v97
	ds_bpermute_b32 v97, v165, v96
	v_cvt_pk_bf16_f32 v100, v108, v109
	v_cvt_pk_bf16_f32 v101, v110, v111
	global_store_dwordx4 v[156:157], v[104:107], off
	global_store_dwordx4 v[156:157], v[98:101], off offset:256
	s_and_saveexec_b64 s[2:3], s[4:5]
	s_cbranch_execz .LBB0_971
	s_waitcnt lgkmcnt(0)
	v_add_f32_e32 v96, v96, v97
	v_mov_b32_e32 v231, v96
; __device__ __forceinline__ unsigned pk2(float lo, float hi) { f32x2_t v = {lo, hi}; bf16x2_t b = __builtin_convertvector(v, bf16x2_t); return __builtin_bit_cast(unsigned, b); }
;     __device__ __forceinline__ float apply(int row, int col, float (&v)[8], const Pre& p) const {
;         const size_t off = (size_t)row * 2048 + col;
;         f32x4 h0, h1; float s = 0.f;
; #pragma unroll
;         for (int i = 0; i < 4; ++i) { h0[i] = p.x0[i] + v[i]; h1[i] = p.x1[i] + v[4 + i]; s += h0[i] * h0[i] + h1[i] * h1[i]; }
;     ...
;         *(f32x4*)(H1 + off) = h0; *(f32x4*)(H1 + off + 4) = h1;
;     ...
;         u32x4 w; w.x = pk2(h0[0], h0[1]); w.y = pk2(h0[2], h0[3]); w.z = pk2(h1[0], h1[1]); w.w = pk2(h1[2], h1[3]);
;         *(u32x4*)(HB + off) = w;
;         return s;
;     __device__ __forceinline__ void operator()(const pg8::f32x4 (&acc)[2][2][4][2], const pg8::Unit& u, int wr, int wc, int fr, int fq) const {
;     ...
;         f.load(row0, col0, pa[0]); f.load(row0, col0 + 128, pa[1]);
; #pragma unroll
;         for (int g = 0; g < 8; ++g) {
;             const int ai = g >> 2, m = g & 3, row = row0 + ai * 128 + m * 16;
;             if (g < 7) { const int row2 = row0 + ((g + 1) >> 2) * 128 + ((g + 1) & 3) * 16;
;                 if (g & 1) { f.load(row2, col0, pa[0]); f.load(row2, col0 + 128, pa[1]); } else { f.load(row2, col0, pb[0]); f.load(row2, col0 + 128, pb[1]); } }
;             float ss = 0.f;
; #pragma unroll
;             for (int bj = 0; bj < 2; ++bj) {
;                 float v[8] = {acc[ai][bj][m][0][0], acc[ai][bj][m][0][1], acc[ai][bj][m][0][2], acc[ai][bj][m][0][3], acc[ai][bj][m][1][0], acc[ai][bj][m][1][1], acc[ai][bj][m][1][2], acc[ai][bj][m][1][3]};
;                 ss += f.apply(row, col0 + bj * 128, v, (g & 1) ? pb[bj] : pa[bj]);
;             }
;             if (F::HAS_SS) { ss += __shfl_xor(ss, 16); ss += __shfl_xor(ss, 32); if (fq == 0) atomicAdd(f.ss + row, ss); }
.LBB0_971:
	s_or_b64 exec, exec, s[2:3]
	v_or_b32_e32 v96, 48, v154
	s_waitcnt lgkmcnt(0)
	v_ashrrev_i32_e32 v97, 31, v96
	v_lshlrev_b64 v[96:97], 12, v[96:97]
	v_lshl_add_u64 v[96:97], s[82:83], 0, v[96:97]
	v_lshl_add_u64 v[104:105], v[152:153], 1, v[96:97]
	global_load_dwordx4 v[100:103], v[104:105], off
	global_load_dwordx4 v[96:99], v[104:105], off offset:256
	s_waitcnt vmcnt(5)
	v_lshlrev_b32_e32 v106, 16, v116
	v_and_b32_e32 v107, 0xffff0000, v116
	v_lshlrev_b32_e32 v110, 16, v118
	v_and_b32_e32 v111, 0xffff0000, v118
	v_lshlrev_b32_e32 v108, 16, v117
	v_and_b32_e32 v109, 0xffff0000, v117
	v_lshlrev_b32_e32 v116, 16, v119
	v_and_b32_e32 v117, 0xffff0000, v119
	v_pk_add_f32 v[92:93], v[92:93], v[106:107]
	v_pk_add_f32 v[106:107], v[88:89], v[110:111]
	v_pk_add_f32 v[94:95], v[94:95], v[108:109]
	v_pk_mul_f32 v[88:89], v[106:107], v[106:107]
	v_pk_add_f32 v[108:109], v[90:91], v[116:117]
	s_waitcnt vmcnt(4)
	v_lshlrev_b32_e32 v124, 16, v114
	v_and_b32_e32 v125, 0xffff0000, v114
	v_pk_fma_f32 v[110:111], v[92:93], v[92:93], v[88:89]
	v_pk_mul_f32 v[88:89], v[108:109], v[108:109]
	v_lshlrev_b32_e32 v118, 16, v112
	v_and_b32_e32 v119, 0xffff0000, v112
	v_lshlrev_b32_e32 v114, 16, v115
	v_and_b32_e32 v115, 0xffff0000, v115
	v_pk_fma_f32 v[90:91], v[94:95], v[94:95], v[88:89]
	v_cvt_pk_bf16_f32 v88, v92, v93
	v_pk_add_f32 v[92:93], v[80:81], v[124:125]
	v_lshlrev_b32_e32 v112, 16, v113
	v_and_b32_e32 v113, 0xffff0000, v113
	v_cvt_pk_bf16_f32 v89, v94, v95
	v_pk_add_f32 v[84:85], v[84:85], v[118:119]
	v_pk_mul_f32 v[80:81], v[92:93], v[92:93]
	v_pk_add_f32 v[94:95], v[82:83], v[114:115]
	v_pk_fma_f32 v[80:81], v[84:85], v[84:85], v[80:81]
	v_pk_add_f32 v[86:87], v[86:87], v[112:113]
	v_pk_mul_f32 v[82:83], v[94:95], v[94:95]
	v_add_f32_e32 v80, v80, v81
	v_pk_fma_f32 v[82:83], v[86:87], v[86:87], v[82:83]
	v_add_f32_e32 v81, v110, v111
	v_add_f32_e32 v80, v82, v80
	v_add_f32_e32 v81, v90, v81
	v_add_f32_e32 v80, v83, v80
	v_add_f32_e32 v81, v91, v81
	v_add_f32_e32 v80, v81, v80
	ds_bpermute_b32 v81, v166, v80
	v_cvt_pk_bf16_f32 v90, v106, v107
	v_cvt_pk_bf16_f32 v91, v108, v109
	v_cvt_pk_bf16_f32 v82, v84, v85
	v_cvt_pk_bf16_f32 v83, v86, v87
	s_waitcnt lgkmcnt(0)
	v_add_f32_e32 v80, v80, v81
	ds_bpermute_b32 v81, v165, v80
	v_cvt_pk_bf16_f32 v84, v92, v93
	v_cvt_pk_bf16_f32 v85, v94, v95
	global_store_dwordx4 v[122:123], v[88:91], off
	global_store_dwordx4 v[122:123], v[82:85], off offset:256
	s_and_saveexec_b64 s[2:3], s[4:5]
	s_cbranch_execz .LBB0_973
	s_waitcnt lgkmcnt(0)
	v_add_f32_e32 v80, v80, v81
	v_mov_b32_e32 v232, v80
.LBB0_973:
	s_or_b64 exec, exec, s[2:3]
	v_add_u32_e32 v88, 0x80, v154
	v_ashrrev_i32_e32 v89, 31, v88
	s_waitcnt lgkmcnt(0)
	v_lshlrev_b64 v[80:81], 12, v[88:89]
	v_lshl_add_u64 v[80:81], s[82:83], 0, v[80:81]
	v_lshl_add_u64 v[90:91], v[152:153], 1, v[80:81]
	global_load_dwordx4 v[84:87], v[90:91], off
	global_load_dwordx4 v[80:83], v[90:91], off offset:256
	s_waitcnt vmcnt(5)
	v_lshlrev_b32_e32 v92, 16, v100
	v_and_b32_e32 v93, 0xffff0000, v100
	v_lshlrev_b32_e32 v94, 16, v101
	v_and_b32_e32 v95, 0xffff0000, v101
	v_lshlrev_b32_e32 v100, 16, v102
	v_and_b32_e32 v101, 0xffff0000, v102
	v_lshlrev_b32_e32 v102, 16, v103
	v_and_b32_e32 v103, 0xffff0000, v103
	v_pk_add_f32 v[76:77], v[76:77], v[92:93]
	v_pk_add_f32 v[92:93], v[72:73], v[100:101]
	v_pk_add_f32 v[78:79], v[78:79], v[94:95]
	v_pk_mul_f32 v[72:73], v[92:93], v[92:93]
	v_pk_add_f32 v[94:95], v[74:75], v[102:103]
	s_waitcnt vmcnt(4)
	v_lshlrev_b32_e32 v108, 16, v98
	v_and_b32_e32 v109, 0xffff0000, v98
	v_pk_fma_f32 v[100:101], v[76:77], v[76:77], v[72:73]
	v_pk_mul_f32 v[72:73], v[94:95], v[94:95]
	v_lshlrev_b32_e32 v106, 16, v96
	v_and_b32_e32 v107, 0xffff0000, v96
	v_lshlrev_b32_e32 v98, 16, v99
	v_and_b32_e32 v99, 0xffff0000, v99
	v_pk_fma_f32 v[74:75], v[78:79], v[78:79], v[72:73]
	v_cvt_pk_bf16_f32 v72, v76, v77
	v_pk_add_f32 v[76:77], v[64:65], v[108:109]
	v_lshlrev_b32_e32 v96, 16, v97
	v_and_b32_e32 v97, 0xffff0000, v97
	v_cvt_pk_bf16_f32 v73, v78, v79
	v_pk_add_f32 v[68:69], v[68:69], v[106:107]
	v_pk_mul_f32 v[64:65], v[76:77], v[76:77]
	v_pk_add_f32 v[78:79], v[66:67], v[98:99]
	v_pk_fma_f32 v[64:65], v[68:69], v[68:69], v[64:65]
	v_pk_add_f32 v[70:71], v[70:71], v[96:97]
	v_pk_mul_f32 v[66:67], v[78:79], v[78:79]
	v_add_f32_e32 v64, v64, v65
	v_pk_fma_f32 v[66:67], v[70:71], v[70:71], v[66:67]
	v_add_f32_e32 v65, v100, v101
	v_add_f32_e32 v64, v66, v64
	v_add_f32_e32 v65, v74, v65
	v_add_f32_e32 v64, v67, v64
	v_add_f32_e32 v65, v75, v65
	v_add_f32_e32 v64, v65, v64
	ds_bpermute_b32 v65, v166, v64
	v_cvt_pk_bf16_f32 v74, v92, v93
	v_cvt_pk_bf16_f32 v75, v94, v95
	v_cvt_pk_bf16_f32 v66, v68, v69
	v_cvt_pk_bf16_f32 v67, v70, v71
	s_waitcnt lgkmcnt(0)
	v_add_f32_e32 v64, v64, v65
	ds_bpermute_b32 v65, v165, v64
	v_cvt_pk_bf16_f32 v68, v76, v77
	v_cvt_pk_bf16_f32 v69, v78, v79
	global_store_dwordx4 v[104:105], v[72:75], off
	global_store_dwordx4 v[104:105], v[66:69], off offset:256
	s_and_saveexec_b64 s[2:3], s[4:5]
	s_cbranch_execz .LBB0_975
	s_waitcnt lgkmcnt(0)
	v_add_f32_e32 v64, v64, v65
	v_mov_b32_e32 v233, v64
; __device__ __forceinline__ unsigned pk2(float lo, float hi) { f32x2_t v = {lo, hi}; bf16x2_t b = __builtin_convertvector(v, bf16x2_t); return __builtin_bit_cast(unsigned, b); }
;     __device__ __forceinline__ float apply(int row, int col, float (&v)[8], const Pre& p) const {
;         const size_t off = (size_t)row * 2048 + col;
;         f32x4 h0, h1; float s = 0.f;
; #pragma unroll
;         for (int i = 0; i < 4; ++i) { h0[i] = p.x0[i] + v[i]; h1[i] = p.x1[i] + v[4 + i]; s += h0[i] * h0[i] + h1[i] * h1[i]; }
;     ...
;         *(f32x4*)(H1 + off) = h0; *(f32x4*)(H1 + off + 4) = h1;
;     ...
;         u32x4 w; w.x = pk2(h0[0], h0[1]); w.y = pk2(h0[2], h0[3]); w.z = pk2(h1[0], h1[1]); w.w = pk2(h1[2], h1[3]);
;         *(u32x4*)(HB + off) = w;
;         return s;
;     __device__ __forceinline__ void operator()(const pg8::f32x4 (&acc)[2][2][4][2], const pg8::Unit& u, int wr, int wc, int fr, int fq) const {
;     ...
;         f.load(row0, col0, pa[0]); f.load(row0, col0 + 128, pa[1]);
; #pragma unroll
;         for (int g = 0; g < 8; ++g) {
;             const int ai = g >> 2, m = g & 3, row = row0 + ai * 128 + m * 16;
;             if (g < 7) { const int row2 = row0 + ((g + 1) >> 2) * 128 + ((g + 1) & 3) * 16;
;                 if (g & 1) { f.load(row2, col0, pa[0]); f.load(row2, col0 + 128, pa[1]); } else { f.load(row2, col0, pb[0]); f.load(row2, col0 + 128, pb[1]); } }
;             float ss = 0.f;
; #pragma unroll
;             for (int bj = 0; bj < 2; ++bj) {
;                 float v[8] = {acc[ai][bj][m][0][0], acc[ai][bj][m][0][1], acc[ai][bj][m][0][2], acc[ai][bj][m][0][3], acc[ai][bj][m][1][0], acc[ai][bj][m][1][1], acc[ai][bj][m][1][2], acc[ai][bj][m][1][3]};
;                 ss += f.apply(row, col0 + bj * 128, v, (g & 1) ? pb[bj] : pa[bj]);
;             }
;             if (F::HAS_SS) { ss += __shfl_xor(ss, 16); ss += __shfl_xor(ss, 32); if (fq == 0) atomicAdd(f.ss + row, ss); }
.LBB0_975:
	s_or_b64 exec, exec, s[2:3]
	v_or_b32_e32 v64, 16, v88
	s_waitcnt lgkmcnt(0)
	v_ashrrev_i32_e32 v65, 31, v64
	v_lshlrev_b64 v[64:65], 12, v[64:65]
	v_lshl_add_u64 v[64:65], s[82:83], 0, v[64:65]
	v_lshl_add_u64 v[72:73], v[152:153], 1, v[64:65]
	global_load_dwordx4 v[68:71], v[72:73], off
	global_load_dwordx4 v[64:67], v[72:73], off offset:256
	s_waitcnt vmcnt(5)
	v_lshlrev_b32_e32 v74, 16, v84
	v_and_b32_e32 v75, 0xffff0000, v84
	v_lshlrev_b32_e32 v78, 16, v86
	v_and_b32_e32 v79, 0xffff0000, v86
	v_lshlrev_b32_e32 v76, 16, v85
	v_and_b32_e32 v77, 0xffff0000, v85
	v_lshlrev_b32_e32 v84, 16, v87
	v_and_b32_e32 v85, 0xffff0000, v87
	v_pk_add_f32 v[60:61], v[60:61], v[74:75]
	v_pk_add_f32 v[74:75], v[56:57], v[78:79]
	v_pk_add_f32 v[62:63], v[62:63], v[76:77]
	v_pk_mul_f32 v[56:57], v[74:75], v[74:75]
	v_pk_add_f32 v[76:77], v[58:59], v[84:85]
	s_waitcnt vmcnt(4)
	v_lshlrev_b32_e32 v92, 16, v82
	v_and_b32_e32 v93, 0xffff0000, v82
	v_pk_fma_f32 v[78:79], v[60:61], v[60:61], v[56:57]
	v_pk_mul_f32 v[56:57], v[76:77], v[76:77]
	v_lshlrev_b32_e32 v86, 16, v80
	v_and_b32_e32 v87, 0xffff0000, v80
	v_lshlrev_b32_e32 v82, 16, v83
	v_and_b32_e32 v83, 0xffff0000, v83
	v_pk_fma_f32 v[58:59], v[62:63], v[62:63], v[56:57]
	v_cvt_pk_bf16_f32 v56, v60, v61
	v_pk_add_f32 v[60:61], v[48:49], v[92:93]
	v_lshlrev_b32_e32 v80, 16, v81
	v_and_b32_e32 v81, 0xffff0000, v81
	v_cvt_pk_bf16_f32 v57, v62, v63
	v_pk_add_f32 v[52:53], v[52:53], v[86:87]
	v_pk_mul_f32 v[48:49], v[60:61], v[60:61]
	v_pk_add_f32 v[62:63], v[50:51], v[82:83]
	v_pk_fma_f32 v[48:49], v[52:53], v[52:53], v[48:49]
	v_pk_add_f32 v[54:55], v[54:55], v[80:81]
	v_pk_mul_f32 v[50:51], v[62:63], v[62:63]
	v_add_f32_e32 v48, v48, v49
	v_pk_fma_f32 v[50:51], v[54:55], v[54:55], v[50:51]
	v_add_f32_e32 v49, v78, v79
	v_add_f32_e32 v48, v50, v48
	v_add_f32_e32 v49, v58, v49
	v_add_f32_e32 v48, v51, v48
	v_add_f32_e32 v49, v59, v49
	v_add_f32_e32 v48, v49, v48
	ds_bpermute_b32 v49, v166, v48
	v_cvt_pk_bf16_f32 v58, v74, v75
	v_cvt_pk_bf16_f32 v59, v76, v77
	v_cvt_pk_bf16_f32 v50, v52, v53
	v_cvt_pk_bf16_f32 v51, v54, v55
	s_waitcnt lgkmcnt(0)
	v_add_f32_e32 v48, v48, v49
	ds_bpermute_b32 v49, v165, v48
	v_cvt_pk_bf16_f32 v52, v60, v61
	v_cvt_pk_bf16_f32 v53, v62, v63
	global_store_dwordx4 v[90:91], v[56:59], off
	global_store_dwordx4 v[90:91], v[50:53], off offset:256
	s_and_saveexec_b64 s[2:3], s[4:5]
	s_cbranch_execz .LBB0_977
	s_waitcnt lgkmcnt(0)
	v_add_f32_e32 v48, v48, v49
	v_mov_b32_e32 v234, v48
.LBB0_977:
	s_or_b64 exec, exec, s[2:3]
	v_or_b32_e32 v48, 32, v88
	s_waitcnt lgkmcnt(0)
	v_ashrrev_i32_e32 v49, 31, v48
	v_lshlrev_b64 v[48:49], 12, v[48:49]
	v_lshl_add_u64 v[48:49], s[82:83], 0, v[48:49]
	v_lshl_add_u64 v[56:57], v[152:153], 1, v[48:49]
	global_load_dwordx4 v[52:55], v[56:57], off
	global_load_dwordx4 v[48:51], v[56:57], off offset:256
	s_waitcnt vmcnt(5)
	v_lshlrev_b32_e32 v58, 16, v68
	v_and_b32_e32 v59, 0xffff0000, v68
	v_lshlrev_b32_e32 v62, 16, v70
	v_and_b32_e32 v63, 0xffff0000, v70
	v_lshlrev_b32_e32 v60, 16, v69
	v_and_b32_e32 v61, 0xffff0000, v69
	v_lshlrev_b32_e32 v68, 16, v71
	v_and_b32_e32 v69, 0xffff0000, v71
	v_pk_add_f32 v[44:45], v[44:45], v[58:59]
	v_pk_add_f32 v[58:59], v[40:41], v[62:63]
	v_pk_add_f32 v[46:47], v[46:47], v[60:61]
	v_pk_mul_f32 v[40:41], v[58:59], v[58:59]
	v_pk_add_f32 v[60:61], v[42:43], v[68:69]
	s_waitcnt vmcnt(4)
	v_lshlrev_b32_e32 v74, 16, v66
	v_and_b32_e32 v75, 0xffff0000, v66
	v_pk_fma_f32 v[62:63], v[44:45], v[44:45], v[40:41]
	v_pk_mul_f32 v[40:41], v[60:61], v[60:61]
	v_lshlrev_b32_e32 v70, 16, v64
	v_and_b32_e32 v71, 0xffff0000, v64
	v_lshlrev_b32_e32 v66, 16, v67
	v_and_b32_e32 v67, 0xffff0000, v67
	v_pk_fma_f32 v[42:43], v[46:47], v[46:47], v[40:41]
	v_cvt_pk_bf16_f32 v40, v44, v45
	v_pk_add_f32 v[44:45], v[32:33], v[74:75]
	v_lshlrev_b32_e32 v64, 16, v65
	v_and_b32_e32 v65, 0xffff0000, v65
	v_cvt_pk_bf16_f32 v41, v46, v47
	v_pk_add_f32 v[36:37], v[36:37], v[70:71]
	v_pk_mul_f32 v[32:33], v[44:45], v[44:45]
	v_pk_add_f32 v[46:47], v[34:35], v[66:67]
	v_pk_fma_f32 v[32:33], v[36:37], v[36:37], v[32:33]
	v_pk_add_f32 v[38:39], v[38:39], v[64:65]
	v_pk_mul_f32 v[34:35], v[46:47], v[46:47]
	v_add_f32_e32 v32, v32, v33
	v_pk_fma_f32 v[34:35], v[38:39], v[38:39], v[34:35]
	v_add_f32_e32 v33, v62, v63
	v_add_f32_e32 v32, v34, v32
	v_add_f32_e32 v33, v42, v33
	v_add_f32_e32 v32, v35, v32
	v_add_f32_e32 v33, v43, v33
	v_add_f32_e32 v32, v33, v32
	ds_bpermute_b32 v33, v166, v32
	v_cvt_pk_bf16_f32 v42, v58, v59
	v_cvt_pk_bf16_f32 v43, v60, v61
	v_cvt_pk_bf16_f32 v34, v36, v37
	v_cvt_pk_bf16_f32 v35, v38, v39
	s_waitcnt lgkmcnt(0)
	v_add_f32_e32 v32, v32, v33
	ds_bpermute_b32 v33, v165, v32
	v_cvt_pk_bf16_f32 v36, v44, v45
	v_cvt_pk_bf16_f32 v37, v46, v47
	global_store_dwordx4 v[72:73], v[40:43], off
	global_store_dwordx4 v[72:73], v[34:37], off offset:256
	s_and_saveexec_b64 s[2:3], s[4:5]
	s_cbranch_execz .LBB0_979
	s_waitcnt lgkmcnt(0)
	v_add_f32_e32 v32, v32, v33
	v_mov_b32_e32 v235, v32
; __device__ __forceinline__ unsigned pk2(float lo, float hi) { f32x2_t v = {lo, hi}; bf16x2_t b = __builtin_convertvector(v, bf16x2_t); return __builtin_bit_cast(unsigned, b); }
;     __device__ __forceinline__ float apply(int row, int col, float (&v)[8], const Pre& p) const {
;         const size_t off = (size_t)row * 2048 + col;
;         f32x4 h0, h1; float s = 0.f;
; #pragma unroll
;         for (int i = 0; i < 4; ++i) { h0[i] = p.x0[i] + v[i]; h1[i] = p.x1[i] + v[4 + i]; s += h0[i] * h0[i] + h1[i] * h1[i]; }
;     ...
;         *(f32x4*)(H1 + off) = h0; *(f32x4*)(H1 + off + 4) = h1;
;     ...
;         u32x4 w; w.x = pk2(h0[0], h0[1]); w.y = pk2(h0[2], h0[3]); w.z = pk2(h1[0], h1[1]); w.w = pk2(h1[2], h1[3]);
;         *(u32x4*)(HB + off) = w;
;         return s;
;     __device__ __forceinline__ void operator()(const pg8::f32x4 (&acc)[2][2][4][2], const pg8::Unit& u, int wr, int wc, int fr, int fq) const {
;     ...
;         f.load(row0, col0, pa[0]); f.load(row0, col0 + 128, pa[1]);
; #pragma unroll
;         for (int g = 0; g < 8; ++g) {
;             const int ai = g >> 2, m = g & 3, row = row0 + ai * 128 + m * 16;
;             if (g < 7) { const int row2 = row0 + ((g + 1) >> 2) * 128 + ((g + 1) & 3) * 16;
;                 if (g & 1) { f.load(row2, col0, pa[0]); f.load(row2, col0 + 128, pa[1]); } else { f.load(row2, col0, pb[0]); f.load(row2, col0 + 128, pb[1]); } }
;             float ss = 0.f;
; #pragma unroll
;             for (int bj = 0; bj < 2; ++bj) {
;                 float v[8] = {acc[ai][bj][m][0][0], acc[ai][bj][m][0][1], acc[ai][bj][m][0][2], acc[ai][bj][m][0][3], acc[ai][bj][m][1][0], acc[ai][bj][m][1][1], acc[ai][bj][m][1][2], acc[ai][bj][m][1][3]};
;                 ss += f.apply(row, col0 + bj * 128, v, (g & 1) ? pb[bj] : pa[bj]);
;             }
;             if (F::HAS_SS) { ss += __shfl_xor(ss, 16); ss += __shfl_xor(ss, 32); if (fq == 0) atomicAdd(f.ss + row, ss); }
.LBB0_979:
	s_or_b64 exec, exec, s[2:3]
	v_or_b32_e32 v32, 48, v88
	s_waitcnt lgkmcnt(0)
	v_ashrrev_i32_e32 v33, 31, v32
	v_lshlrev_b64 v[32:33], 12, v[32:33]
	v_lshl_add_u64 v[32:33], s[82:83], 0, v[32:33]
	v_lshl_add_u64 v[40:41], v[152:153], 1, v[32:33]
	global_load_dwordx4 v[36:39], v[40:41], off
	global_load_dwordx4 v[32:35], v[40:41], off offset:256
	s_waitcnt vmcnt(5)
	v_lshlrev_b32_e32 v42, 16, v52
	v_and_b32_e32 v43, 0xffff0000, v52
	v_lshlrev_b32_e32 v46, 16, v54
	v_and_b32_e32 v47, 0xffff0000, v54
	v_lshlrev_b32_e32 v44, 16, v53
	v_and_b32_e32 v45, 0xffff0000, v53
	v_lshlrev_b32_e32 v52, 16, v55
	v_and_b32_e32 v53, 0xffff0000, v55
	v_pk_add_f32 v[28:29], v[28:29], v[42:43]
	v_pk_add_f32 v[42:43], v[24:25], v[46:47]
	v_pk_add_f32 v[30:31], v[30:31], v[44:45]
	v_pk_mul_f32 v[24:25], v[42:43], v[42:43]
	v_pk_add_f32 v[44:45], v[26:27], v[52:53]
	s_waitcnt vmcnt(4)
	v_lshlrev_b32_e32 v58, 16, v50
	v_and_b32_e32 v59, 0xffff0000, v50
	v_pk_fma_f32 v[46:47], v[28:29], v[28:29], v[24:25]
	v_pk_mul_f32 v[24:25], v[44:45], v[44:45]
	v_lshlrev_b32_e32 v54, 16, v48
	v_and_b32_e32 v55, 0xffff0000, v48
	v_lshlrev_b32_e32 v50, 16, v51
	v_and_b32_e32 v51, 0xffff0000, v51
	v_pk_fma_f32 v[26:27], v[30:31], v[30:31], v[24:25]
	v_cvt_pk_bf16_f32 v24, v28, v29
	v_pk_add_f32 v[28:29], v[16:17], v[58:59]
	v_lshlrev_b32_e32 v48, 16, v49
	v_and_b32_e32 v49, 0xffff0000, v49
	v_cvt_pk_bf16_f32 v25, v30, v31
	v_pk_add_f32 v[20:21], v[20:21], v[54:55]
	v_pk_mul_f32 v[16:17], v[28:29], v[28:29]
	v_pk_add_f32 v[30:31], v[18:19], v[50:51]
	v_pk_fma_f32 v[16:17], v[20:21], v[20:21], v[16:17]
	v_pk_add_f32 v[22:23], v[22:23], v[48:49]
	v_pk_mul_f32 v[18:19], v[30:31], v[30:31]
	v_add_f32_e32 v16, v16, v17
	v_pk_fma_f32 v[18:19], v[22:23], v[22:23], v[18:19]
	v_add_f32_e32 v17, v46, v47
	v_add_f32_e32 v16, v18, v16
	v_add_f32_e32 v17, v26, v17
	v_add_f32_e32 v16, v19, v16
	v_add_f32_e32 v17, v27, v17
	v_add_f32_e32 v16, v17, v16
	ds_bpermute_b32 v17, v166, v16
	v_cvt_pk_bf16_f32 v26, v42, v43
	v_cvt_pk_bf16_f32 v27, v44, v45
	v_cvt_pk_bf16_f32 v18, v20, v21
	v_cvt_pk_bf16_f32 v19, v22, v23
	s_waitcnt lgkmcnt(0)
	v_add_f32_e32 v16, v16, v17
	ds_bpermute_b32 v17, v165, v16
	v_cvt_pk_bf16_f32 v20, v28, v29
	v_cvt_pk_bf16_f32 v21, v30, v31
	global_store_dwordx4 v[56:57], v[24:27], off
	global_store_dwordx4 v[56:57], v[18:21], off offset:256
	s_and_saveexec_b64 s[2:3], s[4:5]
	s_cbranch_execz .LBB0_981
	s_waitcnt lgkmcnt(0)
	v_add_f32_e32 v16, v16, v17
	v_mov_b32_e32 v236, v16
.LBB0_981:
	s_or_b64 exec, exec, s[2:3]
	s_waitcnt vmcnt(3)
	v_lshlrev_b32_e32 v16, 16, v36
	s_waitcnt lgkmcnt(0)
	v_and_b32_e32 v17, 0xffff0000, v36
	v_lshlrev_b32_e32 v20, 16, v38
	v_and_b32_e32 v21, 0xffff0000, v38
	v_lshlrev_b32_e32 v18, 16, v37
	v_and_b32_e32 v19, 0xffff0000, v37
	v_lshlrev_b32_e32 v22, 16, v39
	v_and_b32_e32 v23, 0xffff0000, v39
	v_pk_add_f32 v[12:13], v[12:13], v[16:17]
	v_pk_add_f32 v[16:17], v[8:9], v[20:21]
	v_pk_add_f32 v[14:15], v[14:15], v[18:19]
	v_pk_mul_f32 v[8:9], v[16:17], v[16:17]
	v_pk_add_f32 v[18:19], v[10:11], v[22:23]
	s_waitcnt vmcnt(2)
	v_lshlrev_b32_e32 v28, 16, v34
	v_and_b32_e32 v29, 0xffff0000, v34
	v_pk_fma_f32 v[20:21], v[12:13], v[12:13], v[8:9]
	v_pk_mul_f32 v[8:9], v[18:19], v[18:19]
	v_lshlrev_b32_e32 v24, 16, v32
	v_and_b32_e32 v25, 0xffff0000, v32
	v_lshlrev_b32_e32 v30, 16, v35
	v_and_b32_e32 v31, 0xffff0000, v35
	v_pk_fma_f32 v[10:11], v[14:15], v[14:15], v[8:9]
	v_cvt_pk_bf16_f32 v8, v12, v13
	v_pk_add_f32 v[12:13], v[0:1], v[28:29]
	v_lshlrev_b32_e32 v26, 16, v33
	v_and_b32_e32 v27, 0xffff0000, v33
	v_cvt_pk_bf16_f32 v9, v14, v15
	v_pk_add_f32 v[4:5], v[4:5], v[24:25]
	v_pk_mul_f32 v[0:1], v[12:13], v[12:13]
	v_pk_add_f32 v[14:15], v[2:3], v[30:31]
	v_pk_fma_f32 v[0:1], v[4:5], v[4:5], v[0:1]
	v_pk_add_f32 v[6:7], v[6:7], v[26:27]
	v_pk_mul_f32 v[2:3], v[14:15], v[14:15]
	v_add_f32_e32 v0, v0, v1
	v_pk_fma_f32 v[2:3], v[6:7], v[6:7], v[2:3]
	v_add_f32_e32 v1, v20, v21
	v_add_f32_e32 v0, v2, v0
	v_add_f32_e32 v1, v10, v1
	v_add_f32_e32 v0, v3, v0
	v_add_f32_e32 v1, v11, v1
	v_add_f32_e32 v0, v1, v0
	ds_bpermute_b32 v1, v166, v0
	v_cvt_pk_bf16_f32 v10, v16, v17
	v_cvt_pk_bf16_f32 v11, v18, v19
	v_cvt_pk_bf16_f32 v2, v4, v5
	v_cvt_pk_bf16_f32 v3, v6, v7
	s_waitcnt lgkmcnt(0)
	v_add_f32_e32 v0, v0, v1
	ds_bpermute_b32 v1, v165, v0
	v_cvt_pk_bf16_f32 v4, v12, v13
	v_cvt_pk_bf16_f32 v5, v14, v15
	global_store_dwordx4 v[40:41], v[8:11], off
	global_store_dwordx4 v[40:41], v[2:5], off offset:256
	s_and_saveexec_b64 s[2:3], s[4:5]
	s_cbranch_execz .LBB0_983
	s_waitcnt lgkmcnt(0)
	v_add_f32_e32 v0, v0, v1
	v_mov_b32_e32 v237, v0
	global_atomic_add_f32 v[120:121], v230, off
	global_atomic_add_f32 v[120:121], v231, off offset:64
	global_atomic_add_f32 v[120:121], v232, off offset:128
	global_atomic_add_f32 v[120:121], v233, off offset:192
	global_atomic_add_f32 v[120:121], v234, off offset:512
	global_atomic_add_f32 v[120:121], v235, off offset:576
	global_atomic_add_f32 v[120:121], v236, off offset:640
	global_atomic_add_f32 v[120:121], v237, off offset:704

; #define EDN_LOAD(P, row) do { const float* s_ = H1 + (size_t)(row) * 2048 + col0; P[0][0] = *(const f32x4*)s_; P[0][1] = *(const f32x4*)(s_ + 4); P[1][0] = *(const f32x4*)(s_ + 128); P[1][1] = *(const f32x4*)(s_ + 132); } while (0)
;     __device__ __forceinline__ void operator()(const pg8::f32x4 (&acc)[2][2][4][2], const pg8::Unit& u, int wr, int wc, int fr, int fq) const {
;     ...
;         EDN_LOAD(pa, row0);
; #pragma unroll
;         for (int g = 0; g < 8; ++g) {
;             const int ai = g >> 2, m = g & 3, row = row0 + ai * 128 + m * 16;
;             if (g < 7) { const int row2 = row0 + ((g + 1) >> 2) * 128 + ((g + 1) & 3) * 16; if (g & 1) EDN_LOAD(pa, row2); else EDN_LOAD(pb, row2); }
;             float s = 0.f;
; #pragma unroll
;             for (int bj = 0; bj < 2; ++bj)
; #pragma unroll
;                 for (int n = 0; n < 2; ++n) { const f32x4 hv = h[ai][bj][m][n] + ((g & 1) ? pb[bj][n] : pa[bj][n]); h[ai][bj][m][n] = hv; s += (hv[0] * hv[0] + hv[1] * hv[1]) + (hv[2] * hv[2] + hv[3] * hv[3]); }
;             s += __shfl_xor(s, 16); s += __shfl_xor(s, 32);
;             if (fq == 0) atomicAdd(ss + row, s);
;         }
.LBB0_1127:
	v_lshl_add_u32 v164, s49, 8, v185
	v_ashrrev_i32_e32 v165, 31, v164
	v_lshl_or_b32 v144, s50, 8, v187
	v_lshlrev_b64 v[128:129], 12, v[164:165]
	v_lshl_add_u64 v[128:129], s[82:83], 0, v[128:129]
	v_lshlrev_b32_e32 v130, 1, v144
	v_mov_b32_e32 v131, v145
	v_lshl_add_u64 v[128:129], v[128:129], 0, v[130:131]
	global_load_dwordx4 v[154:157], v[128:129], off
	global_load_dwordx4 v[166:169], v[128:129], off offset:256
	v_or_b32_e32 v160, 16, v164
	v_ashrrev_i32_e32 v161, 31, v160
	v_lshlrev_b64 v[128:129], 12, v[160:161]
	v_lshl_add_u64 v[128:129], s[82:83], 0, v[128:129]
	v_lshl_add_u64 v[128:129], v[128:129], 0, v[130:131]
	global_load_dwordx4 v[132:135], v[128:129], off
	s_nop 0
	global_load_dwordx4 v[128:131], v[128:129], off offset:256
	v_and_b32_e32 v159, 64, v191
	v_xor_b32_e32 v158, 16, v191
	v_add_u32_e32 v174, 64, v159
	v_cmp_lt_i32_e32 vcc, v158, v174
	s_waitcnt vmcnt(0)
	v_and_b32_e32 v159, 0xffff0000, v154
	v_cndmask_b32_e32 v158, v191, v158, vcc
	v_lshlrev_b32_e32 v182, 2, v158
	v_lshlrev_b32_e32 v158, 16, v154
	v_lshlrev_b32_e32 v154, 16, v155
	v_and_b32_e32 v155, 0xffff0000, v155
	v_lshlrev_b32_e32 v162, 16, v156
	v_and_b32_e32 v163, 0xffff0000, v156
	v_lshlrev_b32_e32 v156, 16, v157
	v_and_b32_e32 v157, 0xffff0000, v157
	v_lshlrev_b32_e32 v170, 16, v166
	v_and_b32_e32 v171, 0xffff0000, v166
	v_lshlrev_b32_e32 v166, 16, v167
	v_and_b32_e32 v167, 0xffff0000, v167
	v_lshlrev_b32_e32 v172, 16, v168
	v_and_b32_e32 v173, 0xffff0000, v168
	v_lshlrev_b32_e32 v168, 16, v169
	v_and_b32_e32 v169, 0xffff0000, v169
	v_pk_add_f32 v[126:127], v[126:127], v[154:155]
	v_pk_add_f32 v[124:125], v[124:125], v[158:159]
	v_pk_add_f32 v[122:123], v[122:123], v[156:157]
	v_pk_add_f32 v[120:121], v[120:121], v[162:163]
	v_pk_add_f32 v[154:155], v[118:119], v[166:167]
	v_pk_add_f32 v[156:157], v[116:117], v[170:171]
	v_pk_add_f32 v[158:159], v[114:115], v[168:169]
	v_pk_add_f32 v[162:163], v[112:113], v[172:173]
	v_mul_f32_e32 v112, v125, v125
	v_mul_f32_e32 v113, v127, v127
	v_mul_f32_e32 v114, v121, v121
	v_mul_f32_e32 v115, v123, v123
	v_mul_f32_e32 v116, v157, v157
	v_mul_f32_e32 v117, v155, v155
	v_fmac_f32_e32 v112, v124, v124
	v_fmac_f32_e32 v113, v126, v126
	v_fmac_f32_e32 v114, v120, v120
	v_fmac_f32_e32 v115, v122, v122
	v_mul_f32_e32 v118, v163, v163
	v_mul_f32_e32 v119, v159, v159
	v_fmac_f32_e32 v116, v156, v156
	v_fmac_f32_e32 v117, v154, v154
	v_add_f32_e32 v112, v112, v113
	v_add_f32_e32 v113, v114, v115
	v_fmac_f32_e32 v118, v162, v162
	v_fmac_f32_e32 v119, v158, v158
	v_add_f32_e32 v114, v116, v117
	v_add_f32_e32 v112, v112, v113
	v_add_f32_e32 v112, v112, v114
	v_add_f32_e32 v113, v118, v119
	v_add_f32_e32 v112, v113, v112
	ds_bpermute_b32 v113, v182, v112
	v_xor_b32_e32 v114, 32, v191
	v_cmp_lt_i32_e32 vcc, v114, v174
	v_lshl_add_u64 v[170:171], v[164:165], 2, s[16:17]
	s_waitcnt lgkmcnt(0)
	v_add_f32_e32 v112, v112, v113
	v_cndmask_b32_e32 v114, v191, v114, vcc
	v_lshlrev_b32_e32 v183, 2, v114
	ds_bpermute_b32 v113, v183, v112
	s_and_saveexec_b64 s[0:1], s[4:5]
	s_cbranch_execz .LBB0_1129
	s_waitcnt lgkmcnt(0)
	v_add_f32_e32 v112, v112, v113
	v_mov_b32_e32 v236, v112
	v_lshlrev_b32_e32 v228, 2, v164
.LBB0_1129:
	s_or_b64 exec, exec, s[0:1]
	v_or_b32_e32 v166, 32, v164
	v_ashrrev_i32_e32 v167, 31, v166
	s_waitcnt lgkmcnt(0)
	v_lshlrev_b64 v[112:113], 12, v[166:167]
	v_lshl_add_u64 v[112:113], s[82:83], 0, v[112:113]
	v_lshlrev_b32_e32 v180, 1, v144
	v_mov_b32_e32 v181, v145
	v_lshl_add_u64 v[112:113], v[112:113], 0, v[180:181]
	global_load_dwordx4 v[116:119], v[112:113], off
	s_nop 0
	global_load_dwordx4 v[112:115], v[112:113], off offset:256
	v_lshlrev_b32_e32 v168, 16, v132
	v_and_b32_e32 v169, 0xffff0000, v132
	v_lshlrev_b32_e32 v132, 16, v133
	v_and_b32_e32 v133, 0xffff0000, v133
	v_pk_add_f32 v[110:111], v[110:111], v[132:133]
	v_pk_add_f32 v[108:109], v[108:109], v[168:169]
	v_lshlrev_b32_e32 v174, 16, v128
	v_and_b32_e32 v175, 0xffff0000, v128
	v_lshlrev_b32_e32 v176, 16, v129
	v_and_b32_e32 v177, 0xffff0000, v129
	v_mul_f32_e32 v128, v109, v109
	v_mul_f32_e32 v129, v111, v111
	v_lshlrev_b32_e32 v172, 16, v134
	v_and_b32_e32 v173, 0xffff0000, v134
	v_lshlrev_b32_e32 v134, 16, v135
	v_and_b32_e32 v135, 0xffff0000, v135
	v_fmac_f32_e32 v128, v108, v108
	v_fmac_f32_e32 v129, v110, v110
	v_lshlrev_b32_e32 v178, 16, v130
	v_and_b32_e32 v179, 0xffff0000, v130
	v_add_f32_e32 v130, v128, v129
	v_pk_add_f32 v[106:107], v[106:107], v[134:135]
	v_pk_add_f32 v[128:129], v[104:105], v[172:173]
	v_mul_f32_e32 v105, v107, v107
	v_mul_f32_e32 v104, v129, v129
	v_fmac_f32_e32 v104, v128, v128
	v_fmac_f32_e32 v105, v106, v106
	v_add_f32_e32 v104, v104, v105
	v_lshlrev_b32_e32 v192, 16, v131
	v_and_b32_e32 v193, 0xffff0000, v131
	v_add_f32_e32 v104, v130, v104
	v_pk_add_f32 v[130:131], v[102:103], v[176:177]
	v_pk_add_f32 v[132:133], v[100:101], v[174:175]
	v_mul_f32_e32 v101, v131, v131
	v_mul_f32_e32 v100, v133, v133
	v_pk_add_f32 v[134:135], v[98:99], v[192:193]
	v_pk_add_f32 v[168:169], v[96:97], v[178:179]
	v_fmac_f32_e32 v100, v132, v132
	v_fmac_f32_e32 v101, v130, v130
	v_mul_f32_e32 v96, v169, v169
	v_mul_f32_e32 v97, v135, v135
	v_add_f32_e32 v100, v100, v101
	v_fmac_f32_e32 v96, v168, v168
	v_fmac_f32_e32 v97, v134, v134
	v_add_f32_e32 v100, v104, v100
	v_add_f32_e32 v96, v96, v97
	v_add_f32_e32 v96, v96, v100
	ds_bpermute_b32 v97, v182, v96
	s_waitcnt lgkmcnt(0)
	v_add_f32_e32 v96, v96, v97
	ds_bpermute_b32 v97, v183, v96
	s_and_saveexec_b64 s[0:1], s[4:5]
	s_cbranch_execz .LBB0_1131
	v_lshl_add_u64 v[98:99], v[160:161], 2, s[16:17]
	s_waitcnt lgkmcnt(0)
	v_add_f32_e32 v96, v96, v97
	v_mov_b32_e32 v237, v96
	v_lshlrev_b32_e32 v229, 2, v160
; #define EDN_LOAD(P, row) do { const float* s_ = H1 + (size_t)(row) * 2048 + col0; P[0][0] = *(const f32x4*)s_; P[0][1] = *(const f32x4*)(s_ + 4); P[1][0] = *(const f32x4*)(s_ + 128); P[1][1] = *(const f32x4*)(s_ + 132); } while (0)
;     __device__ __forceinline__ void operator()(const pg8::f32x4 (&acc)[2][2][4][2], const pg8::Unit& u, int wr, int wc, int fr, int fq) const {
;     ...
;         EDN_LOAD(pa, row0);
; #pragma unroll
;         for (int g = 0; g < 8; ++g) {
;             const int ai = g >> 2, m = g & 3, row = row0 + ai * 128 + m * 16;
;             if (g < 7) { const int row2 = row0 + ((g + 1) >> 2) * 128 + ((g + 1) & 3) * 16; if (g & 1) EDN_LOAD(pa, row2); else EDN_LOAD(pb, row2); }
;             float s = 0.f;
; #pragma unroll
;             for (int bj = 0; bj < 2; ++bj)
; #pragma unroll
;                 for (int n = 0; n < 2; ++n) { const f32x4 hv = h[ai][bj][m][n] + ((g & 1) ? pb[bj][n] : pa[bj][n]); h[ai][bj][m][n] = hv; s += (hv[0] * hv[0] + hv[1] * hv[1]) + (hv[2] * hv[2] + hv[3] * hv[3]); }
;             s += __shfl_xor(s, 16); s += __shfl_xor(s, 32);
;             if (fq == 0) atomicAdd(ss + row, s);
;         }
.LBB0_1131:
	s_or_b64 exec, exec, s[0:1]
	v_or_b32_e32 v104, 48, v164
	v_ashrrev_i32_e32 v105, 31, v104
	s_waitcnt lgkmcnt(0)
	v_lshlrev_b64 v[96:97], 12, v[104:105]
	v_lshl_add_u64 v[96:97], s[82:83], 0, v[96:97]
	v_lshl_add_u64 v[96:97], v[96:97], 0, v[180:181]
	global_load_dwordx4 v[100:103], v[96:97], off
	s_nop 0
	global_load_dwordx4 v[96:99], v[96:97], off offset:256
	s_waitcnt vmcnt(3)
	v_lshlrev_b32_e32 v172, 16, v116
	v_and_b32_e32 v173, 0xffff0000, v116
	v_lshlrev_b32_e32 v116, 16, v117
	v_and_b32_e32 v117, 0xffff0000, v117
	v_lshlrev_b32_e32 v174, 16, v118
	v_and_b32_e32 v175, 0xffff0000, v118
	v_lshlrev_b32_e32 v118, 16, v119
	v_and_b32_e32 v119, 0xffff0000, v119
	s_waitcnt vmcnt(2)
	v_lshlrev_b32_e32 v176, 16, v112
	v_and_b32_e32 v177, 0xffff0000, v112
	v_lshlrev_b32_e32 v178, 16, v113
	v_and_b32_e32 v179, 0xffff0000, v113
	v_lshlrev_b32_e32 v192, 16, v114
	v_and_b32_e32 v193, 0xffff0000, v114
	v_lshlrev_b32_e32 v194, 16, v115
	v_and_b32_e32 v195, 0xffff0000, v115
	v_pk_add_f32 v[94:95], v[94:95], v[116:117]
	v_pk_add_f32 v[114:115], v[92:93], v[172:173]
	v_pk_add_f32 v[112:113], v[90:91], v[118:119]
	v_pk_add_f32 v[118:119], v[88:89], v[174:175]
	v_mul_f32_e32 v92, v115, v115
	v_mul_f32_e32 v93, v95, v95
	v_mul_f32_e32 v88, v119, v119
	v_mul_f32_e32 v89, v113, v113
	v_fmac_f32_e32 v92, v114, v114
	v_fmac_f32_e32 v93, v94, v94
	v_fmac_f32_e32 v88, v118, v118
	v_fmac_f32_e32 v89, v112, v112
	v_add_f32_e32 v92, v92, v93
	v_add_f32_e32 v88, v88, v89
	v_pk_add_f32 v[116:117], v[86:87], v[178:179]
	v_pk_add_f32 v[172:173], v[84:85], v[176:177]
	v_add_f32_e32 v88, v92, v88
	v_mul_f32_e32 v84, v173, v173
	v_mul_f32_e32 v85, v117, v117
	v_pk_add_f32 v[90:91], v[82:83], v[194:195]
	v_pk_add_f32 v[92:93], v[80:81], v[192:193]
	v_fmac_f32_e32 v84, v172, v172
	v_fmac_f32_e32 v85, v116, v116
	v_mul_f32_e32 v80, v93, v93
	v_mul_f32_e32 v81, v91, v91
	v_add_f32_e32 v84, v84, v85
	v_fmac_f32_e32 v80, v92, v92
	v_fmac_f32_e32 v81, v90, v90
	v_add_f32_e32 v84, v88, v84
	v_add_f32_e32 v80, v80, v81
	v_add_f32_e32 v80, v80, v84
	ds_bpermute_b32 v81, v182, v80
	s_waitcnt lgkmcnt(0)
	v_add_f32_e32 v80, v80, v81
	ds_bpermute_b32 v81, v183, v80
	s_and_saveexec_b64 s[0:1], s[4:5]
	s_cbranch_execz .LBB0_1133
	v_lshl_add_u64 v[82:83], v[166:167], 2, s[16:17]
	s_waitcnt lgkmcnt(0)
	v_add_f32_e32 v80, v80, v81
	v_mov_b32_e32 v238, v80
	v_lshlrev_b32_e32 v230, 2, v166
.LBB0_1133:
	s_or_b64 exec, exec, s[0:1]
	v_add_u32_e32 v88, 0x80, v164
	v_ashrrev_i32_e32 v89, 31, v88
	s_waitcnt lgkmcnt(0)
	v_lshlrev_b64 v[80:81], 12, v[88:89]
	v_lshl_add_u64 v[80:81], s[82:83], 0, v[80:81]
	v_mov_b32_e32 v181, v145
	v_lshl_add_u64 v[80:81], v[80:81], 0, v[180:181]
	global_load_dwordx4 v[84:87], v[80:81], off
	s_nop 0
	global_load_dwordx4 v[80:83], v[80:81], off offset:256
	s_waitcnt vmcnt(3)
	v_lshlrev_b32_e32 v174, 16, v100
	v_and_b32_e32 v175, 0xffff0000, v100
	v_lshlrev_b32_e32 v100, 16, v101
	v_and_b32_e32 v101, 0xffff0000, v101
	v_pk_add_f32 v[78:79], v[78:79], v[100:101]
	v_pk_add_f32 v[76:77], v[76:77], v[174:175]
	s_waitcnt vmcnt(2)
	v_lshlrev_b32_e32 v192, 16, v98
	v_and_b32_e32 v193, 0xffff0000, v98
	v_lshlrev_b32_e32 v194, 16, v99
	v_and_b32_e32 v195, 0xffff0000, v99
	v_mul_f32_e32 v98, v77, v77
	v_mul_f32_e32 v99, v79, v79
	v_lshlrev_b32_e32 v176, 16, v102
	v_and_b32_e32 v177, 0xffff0000, v102
	v_lshlrev_b32_e32 v102, 16, v103
	v_and_b32_e32 v103, 0xffff0000, v103
	v_fmac_f32_e32 v98, v76, v76
	v_fmac_f32_e32 v99, v78, v78
	v_add_f32_e32 v100, v98, v99
	v_pk_add_f32 v[74:75], v[74:75], v[102:103]
	v_pk_add_f32 v[98:99], v[72:73], v[176:177]
	v_mul_f32_e32 v73, v75, v75
	v_mul_f32_e32 v72, v99, v99
	v_lshlrev_b32_e32 v178, 16, v96
	v_and_b32_e32 v179, 0xffff0000, v96
	v_lshlrev_b32_e32 v96, 16, v97
	v_and_b32_e32 v97, 0xffff0000, v97
	v_fmac_f32_e32 v72, v98, v98
	v_fmac_f32_e32 v73, v74, v74
	v_add_f32_e32 v72, v72, v73
	v_pk_add_f32 v[96:97], v[70:71], v[96:97]
	v_pk_add_f32 v[102:103], v[68:69], v[178:179]
	v_add_f32_e32 v72, v100, v72
	v_mul_f32_e32 v68, v103, v103
	v_mul_f32_e32 v69, v97, v97
	v_pk_add_f32 v[100:101], v[66:67], v[194:195]
	v_pk_add_f32 v[174:175], v[64:65], v[192:193]
	v_fmac_f32_e32 v68, v102, v102
	v_fmac_f32_e32 v69, v96, v96
	v_mul_f32_e32 v64, v175, v175
	v_mul_f32_e32 v65, v101, v101
	v_add_f32_e32 v68, v68, v69
	v_fmac_f32_e32 v64, v174, v174
	v_fmac_f32_e32 v65, v100, v100
	v_add_f32_e32 v68, v72, v68
	v_add_f32_e32 v64, v64, v65
	v_add_f32_e32 v64, v64, v68
	ds_bpermute_b32 v65, v182, v64
	s_waitcnt lgkmcnt(0)
	v_add_f32_e32 v64, v64, v65
	ds_bpermute_b32 v65, v183, v64
	s_and_saveexec_b64 s[0:1], s[4:5]
	s_cbranch_execz .LBB0_1135
	v_lshl_add_u64 v[66:67], v[104:105], 2, s[16:17]
	s_waitcnt lgkmcnt(0)
	v_add_f32_e32 v64, v64, v65
	v_mov_b32_e32 v239, v64
	v_lshlrev_b32_e32 v231, 2, v104
; #define EDN_LOAD(P, row) do { const float* s_ = H1 + (size_t)(row) * 2048 + col0; P[0][0] = *(const f32x4*)s_; P[0][1] = *(const f32x4*)(s_ + 4); P[1][0] = *(const f32x4*)(s_ + 128); P[1][1] = *(const f32x4*)(s_ + 132); } while (0)
;     __device__ __forceinline__ void operator()(const pg8::f32x4 (&acc)[2][2][4][2], const pg8::Unit& u, int wr, int wc, int fr, int fq) const {
;     ...
;         EDN_LOAD(pa, row0);
; #pragma unroll
;         for (int g = 0; g < 8; ++g) {
;             const int ai = g >> 2, m = g & 3, row = row0 + ai * 128 + m * 16;
;             if (g < 7) { const int row2 = row0 + ((g + 1) >> 2) * 128 + ((g + 1) & 3) * 16; if (g & 1) EDN_LOAD(pa, row2); else EDN_LOAD(pb, row2); }
;             float s = 0.f;
; #pragma unroll
;             for (int bj = 0; bj < 2; ++bj)
; #pragma unroll
;                 for (int n = 0; n < 2; ++n) { const f32x4 hv = h[ai][bj][m][n] + ((g & 1) ? pb[bj][n] : pa[bj][n]); h[ai][bj][m][n] = hv; s += (hv[0] * hv[0] + hv[1] * hv[1]) + (hv[2] * hv[2] + hv[3] * hv[3]); }
;             s += __shfl_xor(s, 16); s += __shfl_xor(s, 32);
;             if (fq == 0) atomicAdd(ss + row, s);
;         }
.LBB0_1135:
	s_or_b64 exec, exec, s[0:1]
	v_or_b32_e32 v72, 16, v88
	v_ashrrev_i32_e32 v73, 31, v72
	s_waitcnt lgkmcnt(0)
	v_lshlrev_b64 v[64:65], 12, v[72:73]
	v_lshl_add_u64 v[64:65], s[82:83], 0, v[64:65]
	v_lshl_add_u64 v[64:65], v[64:65], 0, v[180:181]
	global_load_dwordx4 v[68:71], v[64:65], off
	s_nop 0
	global_load_dwordx4 v[64:67], v[64:65], off offset:256
	s_waitcnt vmcnt(3)
	v_lshlrev_b32_e32 v176, 16, v84
	v_and_b32_e32 v177, 0xffff0000, v84
	v_lshlrev_b32_e32 v84, 16, v85
	v_and_b32_e32 v85, 0xffff0000, v85
	v_pk_add_f32 v[62:63], v[62:63], v[84:85]
	v_pk_add_f32 v[60:61], v[60:61], v[176:177]
	s_waitcnt vmcnt(2)
	v_lshlrev_b32_e32 v194, 16, v82
	v_and_b32_e32 v195, 0xffff0000, v82
	v_lshlrev_b32_e32 v196, 16, v83
	v_and_b32_e32 v197, 0xffff0000, v83
	v_mul_f32_e32 v82, v61, v61
	v_mul_f32_e32 v83, v63, v63
	v_lshlrev_b32_e32 v178, 16, v86
	v_and_b32_e32 v179, 0xffff0000, v86
	v_lshlrev_b32_e32 v86, 16, v87
	v_and_b32_e32 v87, 0xffff0000, v87
	v_fmac_f32_e32 v82, v60, v60
	v_fmac_f32_e32 v83, v62, v62
	v_add_f32_e32 v84, v82, v83
	v_pk_add_f32 v[58:59], v[58:59], v[86:87]
	v_pk_add_f32 v[82:83], v[56:57], v[178:179]
	v_mul_f32_e32 v57, v59, v59
	v_mul_f32_e32 v56, v83, v83
	v_lshlrev_b32_e32 v192, 16, v80
	v_and_b32_e32 v193, 0xffff0000, v80
	v_lshlrev_b32_e32 v80, 16, v81
	v_and_b32_e32 v81, 0xffff0000, v81
	v_fmac_f32_e32 v56, v82, v82
	v_fmac_f32_e32 v57, v58, v58
	v_add_f32_e32 v56, v56, v57
	v_pk_add_f32 v[80:81], v[54:55], v[80:81]
	v_pk_add_f32 v[86:87], v[52:53], v[192:193]
	v_add_f32_e32 v56, v84, v56
	v_mul_f32_e32 v52, v87, v87
	v_mul_f32_e32 v53, v81, v81
	v_pk_add_f32 v[84:85], v[50:51], v[196:197]
	v_pk_add_f32 v[176:177], v[48:49], v[194:195]
	v_fmac_f32_e32 v52, v86, v86
	v_fmac_f32_e32 v53, v80, v80
	v_mul_f32_e32 v48, v177, v177
	v_mul_f32_e32 v49, v85, v85
	v_add_f32_e32 v52, v52, v53
	v_fmac_f32_e32 v48, v176, v176
	v_fmac_f32_e32 v49, v84, v84
	v_add_f32_e32 v52, v56, v52
	v_add_f32_e32 v48, v48, v49
	v_add_f32_e32 v48, v48, v52
	ds_bpermute_b32 v49, v182, v48
	s_waitcnt lgkmcnt(0)
	v_add_f32_e32 v48, v48, v49
	ds_bpermute_b32 v49, v183, v48
	s_and_saveexec_b64 s[0:1], s[4:5]
	s_cbranch_execz .LBB0_1137
	v_lshl_add_u64 v[50:51], v[88:89], 2, s[16:17]
	s_waitcnt lgkmcnt(0)
	v_add_f32_e32 v48, v48, v49
	v_mov_b32_e32 v240, v48
	v_lshlrev_b32_e32 v232, 2, v88
.LBB0_1137:
	s_or_b64 exec, exec, s[0:1]
	v_or_b32_e32 v56, 32, v88
	v_ashrrev_i32_e32 v57, 31, v56
	s_waitcnt lgkmcnt(0)
	v_lshlrev_b64 v[48:49], 12, v[56:57]
	v_lshl_add_u64 v[48:49], s[82:83], 0, v[48:49]
	v_mov_b32_e32 v181, v145
	v_lshl_add_u64 v[48:49], v[48:49], 0, v[180:181]
	global_load_dwordx4 v[52:55], v[48:49], off
	s_nop 0
	global_load_dwordx4 v[48:51], v[48:49], off offset:256
	s_waitcnt vmcnt(3)
	v_lshlrev_b32_e32 v178, 16, v68
	v_and_b32_e32 v179, 0xffff0000, v68
	v_lshlrev_b32_e32 v68, 16, v69
	v_and_b32_e32 v69, 0xffff0000, v69
	v_pk_add_f32 v[46:47], v[46:47], v[68:69]
	v_pk_add_f32 v[44:45], v[44:45], v[178:179]
	s_waitcnt vmcnt(2)
	v_lshlrev_b32_e32 v196, 16, v66
	v_and_b32_e32 v197, 0xffff0000, v66
	v_lshlrev_b32_e32 v198, 16, v67
	v_and_b32_e32 v199, 0xffff0000, v67
	v_mul_f32_e32 v66, v45, v45
	v_mul_f32_e32 v67, v47, v47
	v_lshlrev_b32_e32 v192, 16, v70
	v_and_b32_e32 v193, 0xffff0000, v70
	v_lshlrev_b32_e32 v70, 16, v71
	v_and_b32_e32 v71, 0xffff0000, v71
	v_fmac_f32_e32 v66, v44, v44
	v_fmac_f32_e32 v67, v46, v46
	v_add_f32_e32 v68, v66, v67
	v_pk_add_f32 v[42:43], v[42:43], v[70:71]
	v_pk_add_f32 v[66:67], v[40:41], v[192:193]
	v_mul_f32_e32 v41, v43, v43
	v_mul_f32_e32 v40, v67, v67
	v_lshlrev_b32_e32 v194, 16, v64
	v_and_b32_e32 v195, 0xffff0000, v64
	v_lshlrev_b32_e32 v64, 16, v65
	v_and_b32_e32 v65, 0xffff0000, v65
	v_fmac_f32_e32 v40, v66, v66
	v_fmac_f32_e32 v41, v42, v42
	v_add_f32_e32 v40, v40, v41
	v_pk_add_f32 v[64:65], v[38:39], v[64:65]
	v_pk_add_f32 v[70:71], v[36:37], v[194:195]
	v_add_f32_e32 v40, v68, v40
	v_mul_f32_e32 v36, v71, v71
	v_mul_f32_e32 v37, v65, v65
	v_pk_add_f32 v[68:69], v[34:35], v[198:199]
	v_pk_add_f32 v[178:179], v[32:33], v[196:197]
	v_fmac_f32_e32 v36, v70, v70
	v_fmac_f32_e32 v37, v64, v64
	v_mul_f32_e32 v32, v179, v179
	v_mul_f32_e32 v33, v69, v69
	v_add_f32_e32 v36, v36, v37
	v_fmac_f32_e32 v32, v178, v178
	v_fmac_f32_e32 v33, v68, v68
	v_add_f32_e32 v36, v40, v36
	v_add_f32_e32 v32, v32, v33
	v_add_f32_e32 v32, v32, v36
	ds_bpermute_b32 v33, v182, v32
	s_waitcnt lgkmcnt(0)
	v_add_f32_e32 v32, v32, v33
	ds_bpermute_b32 v33, v183, v32
	s_and_saveexec_b64 s[0:1], s[4:5]
	s_cbranch_execz .LBB0_1139
	v_lshl_add_u64 v[34:35], v[72:73], 2, s[16:17]
	s_waitcnt lgkmcnt(0)
	v_add_f32_e32 v32, v32, v33
	v_mov_b32_e32 v241, v32
	v_lshlrev_b32_e32 v233, 2, v72
; #define EDN_LOAD(P, row) do { const float* s_ = H1 + (size_t)(row) * 2048 + col0; P[0][0] = *(const f32x4*)s_; P[0][1] = *(const f32x4*)(s_ + 4); P[1][0] = *(const f32x4*)(s_ + 128); P[1][1] = *(const f32x4*)(s_ + 132); } while (0)
;     __device__ __forceinline__ void operator()(const pg8::f32x4 (&acc)[2][2][4][2], const pg8::Unit& u, int wr, int wc, int fr, int fq) const {
;     ...
;         EDN_LOAD(pa, row0);
; #pragma unroll
;         for (int g = 0; g < 8; ++g) {
;             const int ai = g >> 2, m = g & 3, row = row0 + ai * 128 + m * 16;
;             if (g < 7) { const int row2 = row0 + ((g + 1) >> 2) * 128 + ((g + 1) & 3) * 16; if (g & 1) EDN_LOAD(pa, row2); else EDN_LOAD(pb, row2); }
;             float s = 0.f;
; #pragma unroll
;             for (int bj = 0; bj < 2; ++bj)
; #pragma unroll
;                 for (int n = 0; n < 2; ++n) { const f32x4 hv = h[ai][bj][m][n] + ((g & 1) ? pb[bj][n] : pa[bj][n]); h[ai][bj][m][n] = hv; s += (hv[0] * hv[0] + hv[1] * hv[1]) + (hv[2] * hv[2] + hv[3] * hv[3]); }
;             s += __shfl_xor(s, 16); s += __shfl_xor(s, 32);
;             if (fq == 0) atomicAdd(ss + row, s);
;         }
.LBB0_1139:
	s_or_b64 exec, exec, s[0:1]
	v_or_b32_e32 v40, 48, v88
	v_ashrrev_i32_e32 v41, 31, v40
	s_waitcnt lgkmcnt(0)
	v_lshlrev_b64 v[32:33], 12, v[40:41]
	v_lshl_add_u64 v[32:33], s[82:83], 0, v[32:33]
	v_lshl_add_u64 v[32:33], v[32:33], 0, v[180:181]
	global_load_dwordx4 v[36:39], v[32:33], off
	s_nop 0
	global_load_dwordx4 v[32:35], v[32:33], off offset:256
	s_waitcnt vmcnt(3)
	v_lshlrev_b32_e32 v180, 16, v52
	v_and_b32_e32 v181, 0xffff0000, v52
	v_lshlrev_b32_e32 v52, 16, v53
	v_and_b32_e32 v53, 0xffff0000, v53
	v_pk_add_f32 v[30:31], v[30:31], v[52:53]
	v_pk_add_f32 v[28:29], v[28:29], v[180:181]
	v_lshlrev_b32_e32 v192, 16, v54
	v_and_b32_e32 v193, 0xffff0000, v54
	v_lshlrev_b32_e32 v54, 16, v55
	v_and_b32_e32 v55, 0xffff0000, v55
	s_waitcnt vmcnt(2)
	v_lshlrev_b32_e32 v194, 16, v48
	v_and_b32_e32 v195, 0xffff0000, v48
	v_lshlrev_b32_e32 v48, 16, v49
	v_and_b32_e32 v49, 0xffff0000, v49
	v_mul_f32_e32 v52, v29, v29
	v_mul_f32_e32 v53, v31, v31
	v_fmac_f32_e32 v52, v28, v28
	v_fmac_f32_e32 v53, v30, v30
	v_pk_add_f32 v[26:27], v[26:27], v[54:55]
	v_pk_add_f32 v[24:25], v[24:25], v[192:193]
	v_pk_add_f32 v[22:23], v[22:23], v[48:49]
	v_pk_add_f32 v[20:21], v[20:21], v[194:195]
	v_lshlrev_b32_e32 v196, 16, v50
	v_and_b32_e32 v197, 0xffff0000, v50
	v_lshlrev_b32_e32 v50, 16, v51
	v_and_b32_e32 v51, 0xffff0000, v51
	v_add_f32_e32 v52, v52, v53
	v_mul_f32_e32 v53, v25, v25
	v_mul_f32_e32 v54, v27, v27
	v_mul_f32_e32 v48, v21, v21
	v_mul_f32_e32 v49, v23, v23
	v_fmac_f32_e32 v53, v24, v24
	v_fmac_f32_e32 v54, v26, v26
	v_fmac_f32_e32 v48, v20, v20
	v_fmac_f32_e32 v49, v22, v22
	v_pk_add_f32 v[18:19], v[18:19], v[50:51]
	v_pk_add_f32 v[16:17], v[16:17], v[196:197]
	v_add_f32_e32 v53, v53, v54
	v_add_f32_e32 v48, v48, v49
	v_mul_f32_e32 v49, v17, v17
	v_mul_f32_e32 v50, v19, v19
	v_add_f32_e32 v52, v52, v53
	v_fmac_f32_e32 v49, v16, v16
	v_fmac_f32_e32 v50, v18, v18
	v_add_f32_e32 v48, v52, v48
	v_add_f32_e32 v49, v49, v50
	v_add_f32_e32 v48, v49, v48
	ds_bpermute_b32 v49, v182, v48
	s_waitcnt lgkmcnt(0)
	v_add_f32_e32 v48, v48, v49
	ds_bpermute_b32 v49, v183, v48
	s_and_saveexec_b64 s[0:1], s[4:5]
	s_cbranch_execz .LBB0_1141
	v_lshl_add_u64 v[50:51], v[56:57], 2, s[16:17]
	s_waitcnt lgkmcnt(0)
	v_add_f32_e32 v48, v48, v49
	v_mov_b32_e32 v242, v48
	v_lshlrev_b32_e32 v234, 2, v56
.LBB0_1141:
	s_or_b64 exec, exec, s[0:1]
	s_waitcnt vmcnt(1)
	v_lshlrev_b32_e32 v48, 16, v36
	s_waitcnt lgkmcnt(0)
	v_and_b32_e32 v49, 0xffff0000, v36
	v_lshlrev_b32_e32 v36, 16, v37
	v_and_b32_e32 v37, 0xffff0000, v37
	v_lshlrev_b32_e32 v50, 16, v38
	v_and_b32_e32 v51, 0xffff0000, v38
	v_lshlrev_b32_e32 v38, 16, v39
	v_and_b32_e32 v39, 0xffff0000, v39
	s_waitcnt vmcnt(0)
	v_lshlrev_b32_e32 v52, 16, v32
	v_and_b32_e32 v53, 0xffff0000, v32
	v_lshlrev_b32_e32 v54, 16, v33
	v_and_b32_e32 v55, 0xffff0000, v33
	v_lshlrev_b32_e32 v180, 16, v34
	v_and_b32_e32 v181, 0xffff0000, v34
	v_lshlrev_b32_e32 v192, 16, v35
	v_and_b32_e32 v193, 0xffff0000, v35
	v_pk_add_f32 v[32:33], v[14:15], v[36:37]
	v_pk_add_f32 v[36:37], v[12:13], v[48:49]
	v_pk_add_f32 v[34:35], v[10:11], v[38:39]
	v_pk_add_f32 v[48:49], v[8:9], v[50:51]
	v_mul_f32_e32 v12, v37, v37
	v_mul_f32_e32 v13, v33, v33
	v_mul_f32_e32 v8, v49, v49
	v_mul_f32_e32 v9, v35, v35
	v_pk_add_f32 v[38:39], v[6:7], v[54:55]
	v_pk_add_f32 v[52:53], v[4:5], v[52:53]
	v_fmac_f32_e32 v12, v36, v36
	v_fmac_f32_e32 v13, v32, v32
	v_fmac_f32_e32 v8, v48, v48
	v_fmac_f32_e32 v9, v34, v34
	v_mul_f32_e32 v4, v53, v53
	v_mul_f32_e32 v5, v39, v39
	v_pk_add_f32 v[50:51], v[2:3], v[192:193]
	v_pk_add_f32 v[54:55], v[0:1], v[180:181]
	v_add_f32_e32 v12, v12, v13
	v_add_f32_e32 v8, v8, v9
	v_fmac_f32_e32 v4, v52, v52
	v_fmac_f32_e32 v5, v38, v38
	v_mul_f32_e32 v0, v55, v55
	v_mul_f32_e32 v1, v51, v51
	v_add_f32_e32 v8, v12, v8
	v_add_f32_e32 v4, v4, v5
	v_fmac_f32_e32 v0, v54, v54
	v_fmac_f32_e32 v1, v50, v50
	v_add_f32_e32 v4, v8, v4
	v_add_f32_e32 v0, v0, v1
	v_add_f32_e32 v0, v0, v4
	ds_bpermute_b32 v1, v182, v0
	s_waitcnt lgkmcnt(0)
	v_add_f32_e32 v0, v0, v1
	ds_bpermute_b32 v1, v183, v0
	s_and_saveexec_b64 s[0:1], s[4:5]
	s_cbranch_execz .LBB0_1143
	v_lshl_add_u64 v[2:3], v[40:41], 2, s[16:17]
	s_waitcnt lgkmcnt(0)
	v_add_f32_e32 v0, v0, v1
	v_mov_b32_e32 v243, v0
	v_lshlrev_b32_e32 v235, 2, v40
	global_atomic_add_f32 v228, v236, s[16:17]
	global_atomic_add_f32 v229, v237, s[16:17]
	global_atomic_add_f32 v230, v238, s[16:17]
	global_atomic_add_f32 v231, v239, s[16:17]
	global_atomic_add_f32 v232, v240, s[16:17]
	global_atomic_add_f32 v233, v241, s[16:17]
	global_atomic_add_f32 v234, v242, s[16:17]
	global_atomic_add_f32 v235, v243, s[16:17]
